# deferral made grid-size generic (tail count computed from gridDim at run time); otherwise v14
# baseline (speedup 1.0000x reference)
;     __host__ __device__ bool next(int i, Unit& u) const {
;         const long L = (long)i * G + c; if (L >= nwg) return false;
;         map((int)L, u); return true;
; DI void phase_prologue(const Prm& p, LAS unsigned char* lds, int tid, int lane, int wave) {
;     ...
;     for (int it = gw; it < NITEMS; it += NGW) {
;         int r = it;
;         if (r < I1) { transpose_item(p.w_in_even, 2560, p.Wt1, 1024, p.ln_mix, scr, r, lane); continue; } r -= I1;
;         if (r < I2) { transpose_item(p.w_glu, 512, p.Wglu, 512, nullptr, scr, r, lane); continue; } r -= I2;
;         if (r < I3) { transpose_item(p.w_out_even, 1024, p.Wo0, 1024, nullptr, scr, r, lane); continue; } r -= I3;
;         if (r < I4) { transpose_item(p.w_up, 4096, p.Wup0, 1024, p.ln_mlp, scr, r, lane); continue; } r -= I4;
;         if (r < I5) { transpose_item(p.w_down, 1024, p.Wdn0, 4096, nullptr, scr, r, lane); continue; } r -= I5;
;         if (r < I6) { transpose_item(p.w_in_odd, 3072, p.Wqkv, 1024, p.ln_mix + 1024, scr, r, lane); continue; } r -= I6;
;         if (r < I3) { transpose_item(p.w_out_odd, 1024, p.Wo1, 1024, nullptr, scr, r, lane); continue; } r -= I3;
;         if (r < I4) { transpose_item(p.w_up + (size_t)1024 * 4096, 4096, p.Wup1, 1024, p.ln_mlp + 1024, scr, r, lane); continue; } r -= I4;
;         transpose_item(p.w_down + (size_t)4096 * 1024, 1024, p.Wdn1, 4096, nullptr, scr, r, lane);
;     }
.LBB0_532:
	s_movk_i32 s4, 1310
.Ltr_mod:
	s_cmp_ge_u32 s4, s88
	s_cbranch_scc0 .Ltr_mod_done
	s_sub_u32 s4, s4, s88
	s_branch .Ltr_mod
.Ltr_mod_done:
	s_cmp_lt_u32 s84, s4
	s_cbranch_scc1 .Ltr_skip
	s_sub_u32 s5, s88, s4
	v_mov_b32_e32 v200, v1
	v_mov_b32_e32 v201, v2
	v_mov_b32_e32 v202, v3
	v_mov_b32_e32 v203, v4
	v_mov_b32_e32 v204, v5
	v_mov_b32_e32 v205, v6
	v_mov_b32_e32 v206, v7
	v_mov_b32_e32 v207, v8
	v_mov_b32_e32 v208, v9
	v_mov_b32_e32 v209, v10
	v_mov_b32_e32 v210, v11
	v_mov_b32_e32 v211, v14
	v_mov_b32_e32 v212, v15
	v_mov_b32_e32 v213, v19
	v_mov_b32_e32 v214, v70
	v_mov_b32_e32 v215, v71
	v_mov_b32_e32 v216, v75
	v_mov_b32_e32 v217, v80
	v_mov_b32_e32 v218, v81
	v_mov_b32_e32 v219, v82
	v_mov_b32_e32 v220, v83
	v_writelane_b32 v253, s26, 0
	v_writelane_b32 v253, s27, 1
	v_writelane_b32 v253, s34, 2
	v_writelane_b32 v253, s36, 3
	v_writelane_b32 v253, s37, 4
	v_writelane_b32 v253, s38, 5
	v_writelane_b32 v253, s39, 6
	v_writelane_b32 v253, s40, 7
	v_writelane_b32 v253, s41, 8
	v_writelane_b32 v253, s42, 9
	v_writelane_b32 v253, s43, 10
	v_writelane_b32 v253, s44, 11
	v_writelane_b32 v253, s45, 12
	v_writelane_b32 v253, s46, 13
	v_writelane_b32 v253, s47, 14
	v_writelane_b32 v253, s48, 15
	v_writelane_b32 v253, s49, 16
	v_writelane_b32 v253, s50, 17
	v_writelane_b32 v253, s51, 18
	v_writelane_b32 v253, s53, 19
	v_writelane_b32 v253, s88, 20
	s_mov_b64 s[0:1], s[100:101]
	s_load_dwordx8 s[68:75], s[0:1], 0x40
	s_load_dwordx4 s[24:27], s[0:1], 0xb0
	v_readlane_b32 s96, v254, 50
	v_readlane_b32 s97, v254, 52
	v_readlane_b32 s3, v254, 49
	s_sub_u32 s2, s84, s4
	s_lshl_b32 s2, s2, 3
	s_add_u32 s2, s2, s3
	s_addk_i32 s2, 0x500
	s_lshl_b32 s3, s5, 3
	s_nop 0
	v_writelane_b32 v254, s2, 52
	v_writelane_b32 v254, s3, 50
	s_mov_b32 s88, s5
	s_movk_i32 s99, 0x2f7f
	s_mov_b32 s98, 1
	s_waitcnt lgkmcnt(0)
	s_branch .Ltr_entry
